# NSA phase: one static priority raise for waves 4-7 (per-section setprio toggles inside the NSA unit loop removed) so the two co-resident waves stop running their MFMA and softmax sections in lock-step
# baseline (speedup 1.0000x reference)
; #define LAS __attribute__((address_space(3)))
; __device__ __forceinline__ void nsa_phase(LAS unsigned char* lds, const Args& a, const bf16_t* z, const bf16_t* KC, const bf16_t* VCT, const bf16_t* VST, const bf16_t* VWT, bf16_t* A2, int ldo, bool merged) {
;     const int tid = threadIdx.x, lane = tid & 63, wid = __builtin_amdgcn_readfirstlane(tid >> 6);
;     const int l15_ = lane & 15, g4_ = lane >> 4, hr = wid >> 1, qh = wid & 1;
;     LAS float* IMP = (LAS float*)(lds + NS_IMP);
;     LAS unsigned* SELM = (LAS unsigned*)(lds + NS_SELM);
;     LAS unsigned* UNI = (LAS unsigned*)(lds + NS_UNI);
;     const float* gbias = a.in[7];
;     ...
;     const bool kc_resident = (gridDim.x & 31) == 0;
;     if (kc_resident) {
;         const int bg0 = (int)blockIdx.x & 31;
;         __syncthreads();
; #pragma unroll
;         for (int it = 0; it < 4; ++it) {
;             const int row = it * 64 + (tid >> 3), ch = tid & 7;
;             *(LAS u32x4*)(lds + NS_KCL + row * 144 + ch * 16) = *(const u32x4*)(KC + ((size_t)bg0 * 256 + row) * 256 + ch * 8);
;             const int dim = tid >> 3, c16 = (tid & 7) + 8 * it;
;             *(LAS u32x4*)(lds + NS_VCL + dim * 528 + c16 * 16) = *(const u32x4*)(VCT + ((size_t)bg0 * 64 + dim) * 256 + c16 * 8);
;         }
;     }
;     const int nun = merged ? (((int)blockIdx.x < 128) ? 7 : 9) : (2048 * NSA_REP - (int)blockIdx.x + (int)gridDim.x - 1) / (int)gridDim.x;
.LBB0_910:
	v_readlane_b32 s0, v246, 11
	v_readlane_b32 s1, v246, 12
	s_andn2_b64 vcc, exec, s[0:1]
	s_mov_b64 s[4:5], s[92:93]
	s_cbranch_vccnz .LBB0_1122
	v_readfirstlane_b32 s3, v156
	s_and_b32 s9, s2, 31
	s_lshr_b32 s8, s3, 6
	s_cmp_gt_u32 s8, 3
	s_cbranch_scc0 .Lnsa_prio_lo
	s_setprio 2
.Lnsa_prio_lo:
	s_lshr_b32 s0, s3, 7
	s_bfe_u32 s1, s3, 0x10006
	v_and_b32_e32 v0, 7, v156
	s_lshl_b32 s4, s9, 17
	s_add_u32 s4, s30, s4
	v_lshlrev_b32_e32 v6, 4, v0
	v_mov_b32_e32 v0, 0
	v_lshrrev_b32_e32 v1, 3, v156
	s_addc_u32 s5, s31, 0
	v_mov_b32_e32 v7, v0
	v_lshl_add_u64 v[8:9], s[4:5], 0, v[6:7]
	v_lshlrev_b32_e32 v10, 9, v1
	v_mov_b32_e32 v11, v0
	v_lshl_add_u64 v[2:3], v[8:9], 0, v[10:11]
	s_barrier
	global_load_dwordx4 v[2:5], v[2:3], off
	s_lshl_b32 s4, s9, 15
	s_add_u32 s4, s52, s4
	s_addc_u32 s5, s53, 0
	v_lshl_add_u64 v[12:13], s[4:5], 0, v[10:11]
	s_movk_i32 s4, 0x210
	v_mad_u32_u24 v16, v1, s4, 0
	v_mul_u32_u24_e32 v1, 0x90, v1
	v_add3_u32 v1, 0, v6, v1
	v_or_b32_e32 v14, 0x80, v6
	v_mov_b32_e32 v15, v0
	s_and_b64 s[4:5], s[6:7], exec
	s_cselect_b32 s4, 7, 9
	s_lshl_b32 s6, s8, 3
	s_and_b32 s13, s3, 0xffffffc0
	s_or_b32 s3, s6, 1
	s_mulk_i32 s8, 0x820
	s_add_i32 s33, 0, 0x11400
	s_mul_i32 s6, s3, 0x104
	s_add_i32 s7, s33, s8
	s_add_i32 s6, s33, s6
	s_lshl_b32 s95, s1, 5
	s_lshl_b32 s1, s1, 8
	v_writelane_b32 v246, s92, 13
	s_add_i32 s1, s1, 0
	s_or_b32 s8, s13, 16
	v_writelane_b32 v246, s93, 14
	s_or_b32 s9, s13, 24
	s_or_b32 s10, s13, 32
	s_or_b32 s11, s13, 40
	s_or_b32 s12, s13, 48
	s_mov_b32 s71, s13
	v_writelane_b32 v247, s4, 51
	s_lshl_b32 s4, s0, 6
	s_or_b32 s4, s95, s4
	v_writelane_b32 v247, s4, 38
	s_mov_b32 s61, 0
	s_mov_b32 s59, 0x41800000
	s_mov_b32 s56, 2.0
	s_mov_b32 s20, 0x41900000
	s_mov_b32 s54, 0x42080000
	s_mov_b32 s44, 0x42480000
	v_and_b32_e32 v157, 15, v156
	v_lshrrev_b32_e32 v159, 4, v158
	s_movk_i32 s83, 0x90
	v_cmp_eq_u32_e64 s[4:5], 0, v158
	v_mov_b64_e32 v[166:167], s[38:39]
	s_mov_b32 s58, s61
	s_mov_b32 s92, 0xf149f2ca
	s_movk_i32 s35, 0x200
	s_mov_b32 s23, 0xefa18f08
	s_mov_b32 s57, 0x40400000
	s_mov_b32 s21, 0x41980000
	s_mov_b32 s89, 0x41880000
	s_mov_b32 s88, s59
	s_mov_b32 s55, 0x420c0000
	s_mov_b32 s81, 0x42040000
	s_mov_b32 s45, 0x424c0000
	s_mov_b32 s41, 0x42440000
	v_mov_b32_e32 v168, 0
	v_mov_b32_e32 v169, v0
	v_mov_b32_e32 v194, 0xf149f2ca
	v_mov_b32_e32 v195, 0x1040
	v_not_b32_e32 v196, 63
	v_mov_b32_e32 v197, 0x1a00
	s_mov_b32 s62, 0
	s_waitcnt vmcnt(0)
	ds_write_b128 v1, v[2:5]
	v_lshl_add_u64 v[2:3], v[12:13], 0, v[6:7]
	global_load_dwordx4 v[2:5], v[2:3], off
	v_add_u32_e32 v7, v16, v6
	s_waitcnt vmcnt(0)
	ds_write_b128 v7, v[2:5] offset:36864
	v_add_u32_e32 v2, 0x8000, v10
	v_mov_b32_e32 v3, v0
	v_lshl_add_u64 v[2:3], v[8:9], 0, v[2:3]
	global_load_dwordx4 v[2:5], v[2:3], off
	v_add_u32_e32 v7, v16, v14
	s_waitcnt vmcnt(0)
	ds_write_b128 v1, v[2:5] offset:9216
	v_lshl_add_u64 v[2:3], v[12:13], 0, v[14:15]
	global_load_dwordx4 v[2:5], v[2:3], off
	v_or_b32_e32 v14, 0x100, v6
	v_or_b32_e32 v6, 0x180, v6
	s_waitcnt vmcnt(0)
	ds_write_b128 v7, v[2:5] offset:36864
	v_or_b32_e32 v2, 0x10000, v10
	v_mov_b32_e32 v3, v0
	v_lshl_add_u64 v[2:3], v[8:9], 0, v[2:3]
	global_load_dwordx4 v[2:5], v[2:3], off
	v_add_u32_e32 v7, v16, v14
	s_waitcnt vmcnt(0)
	ds_write_b128 v1, v[2:5] offset:18432
	v_lshl_add_u64 v[2:3], v[12:13], 0, v[14:15]
	global_load_dwordx4 v[2:5], v[2:3], off
	s_waitcnt vmcnt(0)
	ds_write_b128 v7, v[2:5] offset:36864
	v_add_u32_e32 v2, 0x18000, v10
	v_mov_b32_e32 v3, v0
	v_lshl_add_u64 v[2:3], v[8:9], 0, v[2:3]
	global_load_dwordx4 v[2:5], v[2:3], off
	v_mov_b32_e32 v7, v0
	s_waitcnt vmcnt(0)
	ds_write_b128 v1, v[2:5] offset:27648
	v_lshl_add_u64 v[2:3], v[12:13], 0, v[6:7]
	global_load_dwordx4 v[2:5], v[2:3], off
	v_add_u32_e32 v1, v16, v6
	s_waitcnt vmcnt(0)
	ds_write_b128 v1, v[2:5] offset:36864
	v_lshlrev_b32_e32 v2, 2, v158
	v_add_u32_e32 v173, s7, v2
	s_lshl_b32 s7, s3, 3
	s_add_i32 s3, s6, 0x104
	v_add_u32_e32 v186, s3, v2
	s_add_i32 s3, s6, 0x208
	v_add_u32_e32 v187, s3, v2
	s_add_i32 s3, s6, 0x30c
	v_add_u32_e32 v188, s3, v2
	s_add_i32 s3, s6, 0x410
	v_add_u32_e32 v175, s6, v2
	v_add_u32_e32 v189, s3, v2
	s_add_i32 s3, s6, 0x514
	s_addk_i32 s6, 0x618
	v_add_u32_e32 v190, s3, v2
	v_add_u32_e32 v191, s6, v2
	s_or_b32 s6, s13, 56
	s_add_i32 s3, s1, 0x21800
	s_add_i32 s1, s1, 0x21880
	s_and_b32 s13, s2, 1
	v_writelane_b32 v246, s1, 15
	s_lshl_b32 s1, s13, 2
	s_add_i32 s14, s0, s1
	s_add_i32 s0, s14, 1
	v_cvt_f32_u32_e32 v2, s0
	s_mov_b32 s0, 0x42fc0000
	v_mov_b32_e32 v3, 0x42800000
	v_writelane_b32 v247, s3, 55
	v_cmp_lt_f32_e32 vcc, s0, v2
	s_bfe_u32 s3, s2, 0x40001
	s_and_b64 s[0:1], vcc, exec
	v_cndmask_b32_e32 v3, 0, v3, vcc
	v_sub_f32_e32 v2, v3, v2
	v_exp_f32_e32 v2, v2
	s_cselect_b32 s0, 0xffffffc0, 0
	s_mul_i32 s1, s14, 3
	s_lshl_b32 s34, s3, 12
	v_ldexp_f32 v2, v2, s0
	s_lshl_b32 s0, s14, 6
	s_add_i32 s15, s1, 0xc00
	s_lshl_b32 s1, s1, 2
	s_add_u32 s16, s50, s1
	s_addc_u32 s17, s51, 0
	v_writelane_b32 v246, s16, 16
	s_lshl_b32 s1, s13, 19
	s_lshl_b32 s3, s3, 20
	v_writelane_b32 v246, s17, 17
	s_or_b32 s1, s3, s1
	v_readlane_b32 s16, v246, 9
	v_readlane_b32 s17, v246, 10
	s_add_u32 s64, s16, s1
	s_addc_u32 s65, s17, 0
	v_readlane_b32 s16, v246, 7
	v_readlane_b32 s17, v246, 8
	s_add_u32 s66, s16, s1
	s_addc_u32 s67, s17, 0
	s_lshl_b32 s1, s14, 7
	s_add_u32 s16, s90, s1
	v_writelane_b32 v246, s90, 18
	s_addc_u32 s17, s91, 0
	s_lshl_b32 s1, s13, 7
	v_writelane_b32 v246, s91, 19
	v_writelane_b32 v246, s16, 20
	s_add_u32 s72, s38, s1
	s_addc_u32 s73, s39, 0
	v_writelane_b32 v246, s17, 21
	s_or_b32 s1, s95, 0xffffffcd
	v_writelane_b32 v246, s1, 22
	s_sub_i32 s1, 0, s95
	s_lshl_b32 s76, s0, 1
	s_add_i32 s0, s7, 0
	v_writelane_b32 v246, s1, 24
	s_add_i32 s0, s0, 0x21800
	v_writelane_b32 v246, s0, 25
	s_add_i32 s0, s8, 0
	s_add_i32 s0, s0, 0x21800
	v_writelane_b32 v246, s0, 26
	s_add_i32 s0, s9, 0
	s_add_i32 s0, s0, 0x21800
	v_writelane_b32 v246, s0, 27
	s_add_i32 s0, s10, 0
	s_add_i32 s0, s0, 0x21800
	v_writelane_b32 v246, s0, 28
	s_add_i32 s0, s11, 0
	s_add_i32 s0, s0, 0x21800
	v_add_u32_e32 v1, 48, v156
	v_mul_f32_e32 v160, 0x3fb8aa3b, v2
	v_mbcnt_lo_u32_b32 v2, -1, 0
	v_writelane_b32 v246, s0, 29
	s_add_i32 s0, s12, 0
	v_and_b32_e32 v1, 63, v1
	s_mov_b32 s90, 0x42000000
	v_mbcnt_hi_u32_b32 v192, -1, v2
	s_add_i32 s0, s0, 0x21800
	s_mov_b32 s91, 0x42400000
	v_and_or_b32 v1, v192, 64, v1
	v_writelane_b32 v246, s0, 30
	s_add_i32 s0, s6, 0
	v_mov_b32_e32 v162, v160
	v_mov_b32_e32 v163, v160
	v_mov_b32_e32 v164, v160
	v_mov_b32_e32 v165, v160
	s_add_i32 s82, 0, 0x21a00
	s_movk_i32 s3, 0x1a00
	s_lshl_b32 s78, s15, 1
	v_lshlrev_b32_e32 v193, 2, v1
	s_add_i32 s93, 0, 0x21a04
	s_add_i32 s0, s0, 0x21800
	s_mov_b32 s80, s90
	s_mov_b32 s40, s91
	v_writelane_b32 v246, s0, 31
	s_branch .LBB0_913

; #define LAS __attribute__((address_space(3)))
; #define MFMA16(a, b, c) __builtin_amdgcn_mfma_f32_16x16x32_bf16(a, b, c, 0, 0, 0)
; template <int MODE> ...
;     ...
;     for (int qs = 0; qs < 2; ++qs) cb[qs] = slope * (float)(key0 + 4 * g4 - tq[qs]) + ((MODE == 1 && !selb[qs]) ? -1e30f : 0.f);
;     __builtin_amdgcn_s_setprio(1);
; #pragma unroll
;     for (int s = 0; s < 4; ++s) {
;         const LAS unsigned char* kp = KT + (s * 16) * 144;
;         const bf16x8 k0 = *(const LAS bf16x8*)kp, k1 = *(const LAS bf16x8*)(kp + 64);
; #pragma unroll
;         for (int qs = 0; qs < 2; ++qs) {
;             f32x4 zz;
; #pragma unroll
;             for (int i = 0; i < 4; ++i) zz[i] = fmaf(slope, (float)(s * 16 + i), cb[qs]);
;             zz = MFMA16(k0, Qf[qs][0], zz);
;             sc[s][qs] = MFMA16(k1, Qf[qs][1], zz);
;         }
;         __builtin_amdgcn_sched_barrier(0);
;     }
;     __builtin_amdgcn_s_setprio(0);
;     if (!full) {
; #pragma unroll
;         for (int qs = 0; qs < 2; ++qs)
; #pragma unroll
;             for (int s = 0; s < 4; ++s)
; #pragma unroll
;                 for (int i = 0; i < 4; ++i) {
;                     const int dist = (tq[qs] - key0 - 4 * g4) - (s * 16 + i);
;                     const bool ok = (MODE == 1) ? (dist >= 0) : (dist >= 0 && dist < 512);
;                     sc[s][qs][i] = ok ? sc[s][qs][i] : -1e30f;
;                 }
.LBB0_1104:
	v_lshrrev_b64 v[92:93], s9, v[124:125]
	v_and_b32_e32 v94, 1, v92
	v_lshrrev_b64 v[92:93], s9, v[128:129]
	s_lshl_b32 s6, s9, 6
	v_mov_b32_e32 v147, v203
	v_mov_b32_e32 v93, v1
	v_add_u32_e32 v148, s6, v141
	v_add_u32_e32 v149, 0, v93
	v_sub_u32_e32 v93, v148, v138
	v_cmp_eq_u32_e32 vcc, 1, v94
	v_sub_u32_e32 v94, v148, v139
	v_cvt_f32_i32_e32 v93, v93
	v_cvt_f32_i32_e32 v94, v94
	v_and_b32_e32 v92, 1, v92
	v_cndmask_b32_e64 v150, v194, 0, vcc
	v_cmp_eq_u32_e32 vcc, 1, v92
	s_cmp_lt_i32 s9, s63
	v_fmac_f32_e32 v150, v160, v93
	v_cndmask_b32_e64 v154, v194, 0, vcc
	v_fmac_f32_e32 v154, v160, v94
	ds_read_b128 v[92:95], v149
	v_fma_f32 v96, 0, v160, v150
	v_add_f32_e32 v97, v160, v150
	v_pk_fma_f32 v[98:99], v[162:163], s[56:57], v[150:151] op_sel_hi:[1,1,0]
	v_fma_f32 v100, 0, v160, v154
	v_add_f32_e32 v101, v160, v154
	v_pk_fma_f32 v[102:103], v[162:163], s[56:57], v[154:155] op_sel_hi:[1,1,0]
	s_waitcnt lgkmcnt(0)
	v_mfma_f32_16x16x32_bf16 v[96:99], v[92:95], v[4:7], v[96:99]
	v_mfma_f32_16x16x32_bf16 v[92:95], v[92:95], v[12:15], v[100:103]
	s_nop 2
	ds_read_b128 v[100:103], v149 offset:64
	s_waitcnt lgkmcnt(0)
	v_mfma_f32_16x16x32_bf16 v[104:107], v[100:103], v[8:11], v[96:99]
	v_mfma_f32_16x16x32_bf16 v[92:95], v[100:103], v[16:19], v[92:95]
	s_nop 1
	ds_read_b128 v[96:99], v149 offset:2304
	v_mov_b32_e32 v161, v160
	v_pk_fma_f32 v[100:101], v[164:165], s[88:89], v[150:151] op_sel_hi:[1,1,0]
	v_pk_fma_f32 v[102:103], v[160:161], s[20:21], v[150:151] op_sel_hi:[1,1,0]
	v_pk_fma_f32 v[108:109], v[164:165], s[88:89], v[154:155] op_sel_hi:[1,1,0]
	v_pk_fma_f32 v[110:111], v[160:161], s[20:21], v[154:155] op_sel_hi:[1,1,0]
	s_waitcnt lgkmcnt(0)
	v_mfma_f32_16x16x32_bf16 v[100:103], v[96:99], v[4:7], v[100:103]
	v_mfma_f32_16x16x32_bf16 v[96:99], v[96:99], v[12:15], v[108:111]
	s_nop 2
	ds_read_b128 v[108:111], v149 offset:2368
	s_waitcnt lgkmcnt(0)
	v_mfma_f32_16x16x32_bf16 v[112:115], v[108:111], v[8:11], v[100:103]
	v_mfma_f32_16x16x32_bf16 v[96:99], v[108:111], v[16:19], v[96:99]
	s_nop 1
	ds_read_b128 v[100:103], v149 offset:4608
	ds_read_b128 v[120:123], v149 offset:4672
	v_pk_fma_f32 v[110:111], v[160:161], s[54:55], v[150:151] op_sel_hi:[1,1,0]
	v_pk_fma_f32 v[108:109], v[164:165], s[80:81], v[150:151] op_sel_hi:[1,1,0]
	v_pk_fma_f32 v[118:119], v[160:161], s[54:55], v[154:155] op_sel_hi:[1,1,0]
	v_pk_fma_f32 v[116:117], v[164:165], s[80:81], v[154:155] op_sel_hi:[1,1,0]
	s_waitcnt lgkmcnt(1)
	v_mfma_f32_16x16x32_bf16 v[108:111], v[100:103], v[4:7], v[108:111]
	v_mfma_f32_16x16x32_bf16 v[100:103], v[100:103], v[12:15], v[116:119]
	s_waitcnt lgkmcnt(0)
	v_mfma_f32_16x16x32_bf16 v[116:119], v[120:123], v[8:11], v[108:111]
	v_mfma_f32_16x16x32_bf16 v[100:103], v[120:123], v[16:19], v[100:103]
	s_nop 3
	ds_read_b128 v[108:111], v149 offset:6912
	v_pk_fma_f32 v[122:123], v[160:161], s[44:45], v[150:151] op_sel_hi:[1,1,0]
	v_pk_fma_f32 v[120:121], v[164:165], s[40:41], v[150:151] op_sel_hi:[1,1,0]
	v_pk_fma_f32 v[152:153], v[160:161], s[44:45], v[154:155] op_sel_hi:[1,1,0]
	v_pk_fma_f32 v[150:151], v[164:165], s[40:41], v[154:155] op_sel_hi:[1,1,0]
	s_waitcnt lgkmcnt(0)
	v_mfma_f32_16x16x32_bf16 v[120:123], v[108:111], v[4:7], v[120:123]
	v_mfma_f32_16x16x32_bf16 v[108:111], v[108:111], v[12:15], v[150:153]
	s_nop 2
	ds_read_b128 v[150:153], v149 offset:6976
	s_waitcnt lgkmcnt(0)
	v_mfma_f32_16x16x32_bf16 v[120:123], v[150:153], v[8:11], v[120:123]
	v_mfma_f32_16x16x32_bf16 v[108:111], v[150:153], v[16:19], v[108:111]
	s_cbranch_scc1 .LBB0_1106
	v_sub_u32_e32 v149, v138, v148
	v_cmp_lt_i32_e32 vcc, -1, v149
	v_or_b32_e32 v149, 1, v148
	v_sub_u32_e32 v150, v138, v149
	v_cndmask_b32_e32 v104, v194, v104, vcc
	v_cmp_lt_i32_e32 vcc, -1, v150
	v_or_b32_e32 v150, 2, v148
	v_sub_u32_e32 v151, v138, v150
	v_cndmask_b32_e32 v105, v194, v105, vcc
	v_cmp_lt_i32_e32 vcc, -1, v151
	v_or_b32_e32 v151, 3, v148
	v_sub_u32_e32 v152, v138, v151
	v_cndmask_b32_e32 v106, v194, v106, vcc
	v_cmp_lt_i32_e32 vcc, -1, v152
	v_add_u32_e32 v152, 16, v148
	v_sub_u32_e32 v153, v138, v152
	v_cndmask_b32_e32 v107, v194, v107, vcc
	v_cmp_lt_i32_e32 vcc, -1, v153
	v_add_u32_e32 v153, 17, v148
	v_sub_u32_e32 v154, v138, v153
	v_cndmask_b32_e32 v112, v194, v112, vcc
	v_cmp_lt_i32_e32 vcc, -1, v154
	v_add_u32_e32 v154, 18, v148
	v_sub_u32_e32 v155, v138, v154
	v_cndmask_b32_e32 v113, v194, v113, vcc
	v_cmp_lt_i32_e32 vcc, -1, v155
	v_add_u32_e32 v155, 19, v148
	v_sub_u32_e32 v161, v138, v155
	v_cndmask_b32_e32 v114, v194, v114, vcc
	v_cmp_lt_i32_e32 vcc, -1, v161
	v_add_u32_e32 v161, 32, v148
	v_sub_u32_e32 v176, v138, v161
	v_cndmask_b32_e32 v115, v194, v115, vcc
	v_cmp_lt_i32_e32 vcc, -1, v176
	v_add_u32_e32 v176, 33, v148
	v_sub_u32_e32 v177, v138, v176
	v_cndmask_b32_e32 v116, v194, v116, vcc
	v_cmp_lt_i32_e32 vcc, -1, v177
	v_add_u32_e32 v177, 34, v148
	v_sub_u32_e32 v178, v138, v177
	v_cndmask_b32_e32 v117, v194, v117, vcc
	v_cmp_lt_i32_e32 vcc, -1, v178
	v_add_u32_e32 v178, 35, v148
	v_sub_u32_e32 v179, v138, v178
	v_cndmask_b32_e32 v118, v194, v118, vcc
	v_cmp_lt_i32_e32 vcc, -1, v179
	v_add_u32_e32 v179, 48, v148
	v_sub_u32_e32 v180, v138, v179
	v_cndmask_b32_e32 v119, v194, v119, vcc
	v_cmp_lt_i32_e32 vcc, -1, v180
	v_add_u32_e32 v180, 49, v148
	v_sub_u32_e32 v181, v138, v180
	v_cndmask_b32_e32 v120, v194, v120, vcc
	v_cmp_lt_i32_e32 vcc, -1, v181
	v_add_u32_e32 v181, 50, v148
	v_sub_u32_e32 v182, v138, v181
	v_cndmask_b32_e32 v121, v194, v121, vcc
	v_cmp_lt_i32_e32 vcc, -1, v182
	v_add_u32_e32 v182, 51, v148
	v_sub_u32_e32 v183, v138, v182
	v_cndmask_b32_e32 v122, v194, v122, vcc
	v_cmp_lt_i32_e32 vcc, -1, v183
	v_sub_u32_e32 v148, v139, v148
; template <int MODE> ...
;     ...
;                     const int dist = (tq[qs] - key0 - 4 * g4) - (s * 16 + i);
;                     const bool ok = (MODE == 1) ? (dist >= 0) : (dist >= 0 && dist < 512);
;                     sc[s][qs][i] = ok ? sc[s][qs][i] : -1e30f;
;                 }
;     }
; #pragma unroll
;     for (int qs = 0; qs < 2; ++qs) {
;         float mx = -1e30f;
; #pragma unroll
;         for (int s = 0; s < 4; ++s)
; #pragma unroll
;             for (int i = 0; i < 4; ++i) mx = fmaxf(mx, sc[s][qs][i]);
;         mx = fmaxf(mx, __shfl_xor(mx, 16)); mx = fmaxf(mx, __shfl_xor(mx, 32));
;         const float mn = fmaxf(mrun[qs], mx);
;         const float alpha = __builtin_amdgcn_exp2f(mrun[qs] - mn);
;         mrun[qs] = mn;
;         const float mnx = fmaxf(mn, -1e29f);
;         float ps = 0.f;
; #pragma unroll
;         for (int s = 0; s < 4; ++s)
; #pragma unroll
;             for (int i = 0; i < 4; ++i) { const float p = __builtin_amdgcn_exp2f(sc[s][qs][i] - mnx); sc[s][qs][i] = p; ps += p; }
	s_nop 0
	v_cndmask_b32_e32 v123, v194, v123, vcc
	v_cmp_lt_i32_e32 vcc, -1, v148
	v_sub_u32_e32 v148, v139, v149
	s_nop 0
	v_cndmask_b32_e32 v92, v194, v92, vcc
	v_cmp_lt_i32_e32 vcc, -1, v148
	v_sub_u32_e32 v148, v139, v150
	s_nop 0
	v_cndmask_b32_e32 v93, v194, v93, vcc
	v_cmp_lt_i32_e32 vcc, -1, v148
	v_sub_u32_e32 v148, v139, v151
	s_nop 0
	v_cndmask_b32_e32 v94, v194, v94, vcc
	v_cmp_lt_i32_e32 vcc, -1, v148
	v_sub_u32_e32 v148, v139, v152
	s_nop 0
	v_cndmask_b32_e32 v95, v194, v95, vcc
	v_cmp_lt_i32_e32 vcc, -1, v148
	v_sub_u32_e32 v148, v139, v153
	s_nop 0
	v_cndmask_b32_e32 v96, v194, v96, vcc
	v_cmp_lt_i32_e32 vcc, -1, v148
	v_sub_u32_e32 v148, v139, v154
	s_nop 0
	v_cndmask_b32_e32 v97, v194, v97, vcc
	v_cmp_lt_i32_e32 vcc, -1, v148
	v_sub_u32_e32 v148, v139, v155
	s_nop 0
	v_cndmask_b32_e32 v98, v194, v98, vcc
	v_cmp_lt_i32_e32 vcc, -1, v148
	v_sub_u32_e32 v148, v139, v161
	s_nop 0
	v_cndmask_b32_e32 v99, v194, v99, vcc
	v_cmp_lt_i32_e32 vcc, -1, v148
	v_sub_u32_e32 v148, v139, v176
	s_nop 0
	v_cndmask_b32_e32 v100, v194, v100, vcc
	v_cmp_lt_i32_e32 vcc, -1, v148
	v_sub_u32_e32 v148, v139, v177
	s_nop 0
	v_cndmask_b32_e32 v101, v194, v101, vcc
	v_cmp_lt_i32_e32 vcc, -1, v148
	v_sub_u32_e32 v148, v139, v178
	s_nop 0
	v_cndmask_b32_e32 v102, v194, v102, vcc
	v_cmp_lt_i32_e32 vcc, -1, v148
	v_sub_u32_e32 v148, v139, v179
	s_nop 0
	v_cndmask_b32_e32 v103, v194, v103, vcc
	v_cmp_lt_i32_e32 vcc, -1, v148
	v_sub_u32_e32 v148, v139, v180
	s_nop 0
	v_cndmask_b32_e32 v108, v194, v108, vcc
	v_cmp_lt_i32_e32 vcc, -1, v148
	v_sub_u32_e32 v148, v139, v181
	s_nop 0
	v_cndmask_b32_e32 v109, v194, v109, vcc
	v_cmp_lt_i32_e32 vcc, -1, v148
	v_sub_u32_e32 v148, v139, v182
	s_nop 0
	v_cndmask_b32_e32 v110, v194, v110, vcc
	v_cmp_lt_i32_e32 vcc, -1, v148
	s_nop 1
	v_cndmask_b32_e32 v111, v194, v111, vcc
.LBB0_1106:
	v_max3_f32 v148, v104, s92, v105
	v_max3_f32 v148, v148, v106, v107
	v_max3_f32 v148, v148, v112, v113
	v_max3_f32 v148, v148, v114, v115
	v_max3_f32 v148, v148, v116, v117
	v_max3_f32 v148, v148, v118, v119
	v_max3_f32 v148, v148, v120, v121
	v_max3_f32 v148, v148, v122, v123
	ds_bpermute_b32 v149, v201, v148
	v_add_u32_e32 v161, 0, v147
	s_waitcnt lgkmcnt(0)
	v_max_f32_e32 v149, v149, v149
	v_max_f32_e32 v148, v148, v149
	ds_bpermute_b32 v149, v202, v148
	s_waitcnt lgkmcnt(0)
	v_max3_f32 v147, v146, v148, v149
	v_max_f32_e32 v148, 0xefa18f08, v147
	v_sub_f32_e32 v106, v106, v148
	v_exp_f32_e32 v153, v106
	v_max3_f32 v106, v92, s92, v93
	v_max3_f32 v106, v106, v94, v95
	v_max3_f32 v106, v106, v96, v97
	v_max3_f32 v106, v106, v98, v99
	v_max3_f32 v106, v106, v100, v101
	v_max3_f32 v106, v106, v102, v103
	v_max3_f32 v106, v106, v108, v109
	v_sub_f32_e32 v104, v104, v148
	v_max3_f32 v106, v106, v110, v111
	v_exp_f32_e32 v149, v104
	v_sub_f32_e32 v104, v112, v148
	ds_bpermute_b32 v112, v201, v106
	v_exp_f32_e32 v177, v104
	v_sub_f32_e32 v104, v113, v148
	v_exp_f32_e32 v179, v104
	v_sub_f32_e32 v104, v114, v148
	s_waitcnt lgkmcnt(0)
	v_max_f32_e32 v112, v112, v112
	v_exp_f32_e32 v181, v104
	v_sub_f32_e32 v104, v115, v148
	v_max_f32_e32 v106, v106, v112
	v_sub_f32_e32 v105, v105, v148
	v_exp_f32_e32 v183, v104
	v_sub_f32_e32 v104, v116, v148
	ds_bpermute_b32 v112, v202, v106
	v_sub_f32_e32 v107, v107, v148
	v_exp_f32_e32 v151, v105
	v_exp_f32_e32 v105, v104
	v_sub_f32_e32 v104, v117, v148
	v_exp_f32_e32 v155, v107
	v_exp_f32_e32 v107, v104
	v_sub_f32_e32 v104, v118, v148
	v_exp_f32_e32 v113, v104
	v_sub_f32_e32 v104, v119, v148
	v_sub_f32_e32 v146, v146, v147
	v_exp_f32_e32 v115, v104
	v_sub_f32_e32 v104, v120, v148
	v_exp_f32_e32 v117, v104
	v_sub_f32_e32 v104, v121, v148
	v_exp_f32_e32 v185, v146
	s_waitcnt lgkmcnt(0)
; #define LAS __attribute__((address_space(3)))
; __device__ __forceinline__ unsigned pk2(float lo, float hi) { f32x2 v = {lo, hi}; bf16x2_t b = __builtin_convertvector(v, bf16x2_t); return __builtin_bit_cast(unsigned, b); }
; #define MFMA16(a, b, c) __builtin_amdgcn_mfma_f32_16x16x32_bf16(a, b, c, 0, 0, 0)
; template <int MODE> ...
;     ...
;         mx = fmaxf(mx, __shfl_xor(mx, 16)); mx = fmaxf(mx, __shfl_xor(mx, 32));
;         const float mn = fmaxf(mrun[qs], mx);
;         const float alpha = __builtin_amdgcn_exp2f(mrun[qs] - mn);
;         mrun[qs] = mn;
;         const float mnx = fmaxf(mn, -1e29f);
;         float ps = 0.f;
; #pragma unroll
;         for (int s = 0; s < 4; ++s)
; #pragma unroll
;             for (int i = 0; i < 4; ++i) { const float p = __builtin_amdgcn_exp2f(sc[s][qs][i] - mnx); sc[s][qs][i] = p; ps += p; }
;         lrun[qs] = lrun[qs] * alpha + ps;
; #pragma unroll
;         for (int d = 0; d < 4; ++d) O[d][qs] = O[d][qs] * alpha;
;     }
;     __builtin_amdgcn_s_setprio(1);
; #pragma unroll
;     for (int kk = 0; kk < 2; ++kk) {
;         bf16x8 Pf[2];
; #pragma unroll
;         for (int qs = 0; qs < 2; ++qs) { u32x4 w; w.x = pk2(sc[2 * kk][qs][0], sc[2 * kk][qs][1]); w.y = pk2(sc[2 * kk][qs][2], sc[2 * kk][qs][3]);
;             w.z = pk2(sc[2 * kk + 1][qs][0], sc[2 * kk + 1][qs][1]); w.w = pk2(sc[2 * kk + 1][qs][2], sc[2 * kk + 1][qs][3]); Pf[qs] = __builtin_bit_cast(bf16x8, w); }
; #pragma unroll
;         for (int d = 0; d < 4; ++d) {
;             const LAS unsigned char* vp = VT + (d * 16) * 144 + (kk * 32) * 2;
;             const s16x4 lo = *(const LAS s16x4*)vp, hi = *(const LAS s16x4*)(vp + 32);
;             const bf16x8 Vf = {lo[0], lo[1], lo[2], lo[3], hi[0], hi[1], hi[2], hi[3]};
; #pragma unroll
;             for (int qs = 0; qs < 2; ++qs) O[d][qs] = MFMA16(Vf, Pf[qs], O[d][qs]);
;             __builtin_amdgcn_sched_barrier(0);
;         }
;     }
	v_max3_f32 v146, v145, v106, v112
	v_exp_f32_e32 v119, v104
	v_sub_f32_e32 v104, v122, v148
	v_max_f32_e32 v122, 0xefa18f08, v146
	v_sub_f32_e32 v92, v92, v122
	v_exp_f32_e32 v121, v104
	v_sub_f32_e32 v104, v123, v148
	v_exp_f32_e32 v148, v92
	v_sub_f32_e32 v92, v93, v122
	v_exp_f32_e32 v150, v92
	v_sub_f32_e32 v92, v94, v122
	v_exp_f32_e32 v152, v92
	v_sub_f32_e32 v92, v95, v122
	v_exp_f32_e32 v154, v92
	v_sub_f32_e32 v92, v96, v122
	v_exp_f32_e32 v176, v92
	v_sub_f32_e32 v92, v97, v122
	v_exp_f32_e32 v178, v92
	v_pk_add_f32 v[92:93], v[148:149], 0 op_sel_hi:[1,0]
	v_sub_f32_e32 v94, v98, v122
	v_pk_add_f32 v[92:93], v[150:151], v[92:93]
	v_exp_f32_e32 v180, v94
	v_pk_add_f32 v[92:93], v[152:153], v[92:93]
	v_sub_f32_e32 v94, v99, v122
	v_pk_add_f32 v[92:93], v[154:155], v[92:93]
	v_exp_f32_e32 v182, v94
	v_sub_f32_e32 v94, v100, v122
	v_exp_f32_e32 v123, v104
	v_pk_add_f32 v[92:93], v[176:177], v[92:93]
	v_exp_f32_e32 v104, v94
	v_sub_f32_e32 v94, v101, v122
	v_pk_add_f32 v[92:93], v[178:179], v[92:93]
	v_exp_f32_e32 v106, v94
	v_sub_f32_e32 v94, v102, v122
	v_exp_f32_e32 v112, v94
	v_sub_f32_e32 v94, v103, v122
	v_pk_add_f32 v[92:93], v[180:181], v[92:93]
	v_exp_f32_e32 v114, v94
	v_sub_f32_e32 v94, v108, v122
	v_pk_add_f32 v[92:93], v[182:183], v[92:93]
	v_exp_f32_e32 v116, v94
	v_sub_f32_e32 v94, v109, v122
	v_pk_add_f32 v[92:93], v[104:105], v[92:93]
	v_exp_f32_e32 v118, v94
	v_sub_f32_e32 v94, v110, v122
	v_pk_add_f32 v[92:93], v[106:107], v[92:93]
	v_exp_f32_e32 v120, v94
	v_sub_f32_e32 v94, v111, v122
	v_pk_add_f32 v[92:93], v[112:113], v[92:93]
	v_sub_f32_e32 v145, v145, v146
	v_exp_f32_e32 v122, v94
	v_pk_add_f32 v[92:93], v[114:115], v[92:93]
	v_exp_f32_e32 v184, v145
	v_pk_add_f32 v[92:93], v[116:117], v[92:93]
	v_mov_b32_e32 v94, v185
	v_pk_add_f32 v[92:93], v[118:119], v[92:93]
	v_pk_mul_f32 v[78:79], v[78:79], v[94:95] op_sel_hi:[1,0]
	v_pk_add_f32 v[92:93], v[120:121], v[92:93]
	v_pk_mul_f32 v[76:77], v[76:77], v[94:95] op_sel_hi:[1,0]
	v_pk_add_f32 v[92:93], v[122:123], v[92:93]
	v_pk_mul_f32 v[82:83], v[82:83], v[94:95] op_sel_hi:[1,0]
	v_pk_mul_f32 v[80:81], v[80:81], v[94:95] op_sel_hi:[1,0]
	v_pk_mul_f32 v[74:75], v[74:75], v[94:95] op_sel_hi:[1,0]
	v_pk_mul_f32 v[72:73], v[72:73], v[94:95] op_sel_hi:[1,0]
	v_pk_mul_f32 v[70:71], v[70:71], v[94:95] op_sel_hi:[1,0]
	v_pk_mul_f32 v[68:69], v[68:69], v[94:95] op_sel_hi:[1,0]
	v_pk_fma_f32 v[134:135], v[134:135], v[184:185], v[92:93]
	v_pk_mul_f32 v[66:67], v[66:67], v[184:185] op_sel_hi:[1,0]
	v_pk_mul_f32 v[64:65], v[64:65], v[184:185] op_sel_hi:[1,0]
	v_pk_mul_f32 v[62:63], v[62:63], v[184:185] op_sel_hi:[1,0]
	v_pk_mul_f32 v[60:61], v[60:61], v[184:185] op_sel_hi:[1,0]
	v_pk_mul_f32 v[58:59], v[58:59], v[184:185] op_sel_hi:[1,0]
	v_pk_mul_f32 v[56:57], v[56:57], v[184:185] op_sel_hi:[1,0]
	v_pk_mul_f32 v[54:55], v[54:55], v[184:185] op_sel_hi:[1,0]
	v_pk_mul_f32 v[52:53], v[52:53], v[184:185] op_sel_hi:[1,0]
	ds_read2_b64 v[100:103], v161 offset1:4
	v_cvt_pk_bf16_f32 v92, v149, v151
	v_cvt_pk_bf16_f32 v93, v153, v155
	v_cvt_pk_bf16_f32 v94, v177, v179
	v_cvt_pk_bf16_f32 v95, v181, v183
	v_cvt_pk_bf16_f32 v96, v148, v150
	v_cvt_pk_bf16_f32 v97, v152, v154
	v_cvt_pk_bf16_f32 v98, v176, v178
	v_cvt_pk_bf16_f32 v99, v180, v182
	s_waitcnt lgkmcnt(0)
	v_mfma_f32_16x16x32_bf16 v[76:79], v[100:103], v[92:95], v[76:79]
	v_mfma_f32_16x16x32_bf16 v[64:67], v[100:103], v[96:99], v[64:67]
	v_add_u32_e32 v108, 0x800, v161
	ds_read2_b64 v[100:103], v108 offset0:32 offset1:36
	s_waitcnt lgkmcnt(0)
	v_mfma_f32_16x16x32_bf16 v[80:83], v[100:103], v[92:95], v[80:83]
	v_mfma_f32_16x16x32_bf16 v[60:63], v[100:103], v[96:99], v[60:63]
	v_add_u32_e32 v109, 0x1000, v161
	ds_read2_b64 v[100:103], v109 offset0:64 offset1:68
	s_waitcnt lgkmcnt(0)
	v_mfma_f32_16x16x32_bf16 v[72:75], v[100:103], v[92:95], v[72:75]
	v_mfma_f32_16x16x32_bf16 v[56:59], v[100:103], v[96:99], v[56:59]
	v_add_u32_e32 v110, 0x1800, v161
	ds_read2_b64 v[100:103], v110 offset0:96 offset1:100
	s_waitcnt lgkmcnt(0)
	v_mfma_f32_16x16x32_bf16 v[68:71], v[100:103], v[92:95], v[68:71]
	v_mfma_f32_16x16x32_bf16 v[52:55], v[100:103], v[96:99], v[52:55]
	ds_read2_b64 v[100:103], v161 offset0:8 offset1:12
	v_cvt_pk_bf16_f32 v92, v105, v107
	v_cvt_pk_bf16_f32 v93, v113, v115
	v_cvt_pk_bf16_f32 v94, v117, v119
	v_cvt_pk_bf16_f32 v95, v121, v123
	v_cvt_pk_bf16_f32 v96, v104, v106
	v_cvt_pk_bf16_f32 v97, v112, v114
	v_cvt_pk_bf16_f32 v98, v116, v118
	v_cvt_pk_bf16_f32 v99, v120, v122
	s_waitcnt lgkmcnt(0)
	v_mfma_f32_16x16x32_bf16 v[76:79], v[100:103], v[92:95], v[76:79]
	v_mfma_f32_16x16x32_bf16 v[64:67], v[100:103], v[96:99], v[64:67]
	ds_read2_b64 v[100:103], v108 offset0:40 offset1:44
	s_waitcnt lgkmcnt(0)
	v_mfma_f32_16x16x32_bf16 v[80:83], v[100:103], v[92:95], v[80:83]
	v_mfma_f32_16x16x32_bf16 v[60:63], v[100:103], v[96:99], v[60:63]
	ds_read2_b64 v[100:103], v109 offset0:72 offset1:76
	s_waitcnt lgkmcnt(0)
	v_mfma_f32_16x16x32_bf16 v[72:75], v[100:103], v[92:95], v[72:75]
	v_mfma_f32_16x16x32_bf16 v[56:59], v[100:103], v[96:99], v[56:59]
	ds_read2_b64 v[100:103], v110 offset0:104 offset1:108
	s_waitcnt lgkmcnt(0)
	v_mfma_f32_16x16x32_bf16 v[68:71], v[100:103], v[92:95], v[68:71]
	v_mfma_f32_16x16x32_bf16 v[52:55], v[100:103], v[96:99], v[52:55]
	s_cmp_lt_i32 s8, 0
	s_cbranch_scc1 .LBB0_1113
	s_mov_b32 s9, s8
	s_mov_b64 s[6:7], s[0:1]
	v_mov_b32_e32 v145, v146
	v_mov_b32_e32 v146, v147
	s_branch .LBB0_1101

; __device__ __forceinline__ unsigned pk2(float lo, float hi) { f32x2 v = {lo, hi}; bf16x2_t b = __builtin_convertvector(v, bf16x2_t); return __builtin_bit_cast(unsigned, b); }
; template <int MODE> ...
;     ...
;     for (int qs = 0; qs < 2; ++qs) {
;         float mx = -1e30f;
; #pragma unroll
;         for (int s = 0; s < 4; ++s)
; #pragma unroll
;             for (int i = 0; i < 4; ++i) mx = fmaxf(mx, sc[s][qs][i]);
;         mx = fmaxf(mx, __shfl_xor(mx, 16)); mx = fmaxf(mx, __shfl_xor(mx, 32));
;         const float mn = fmaxf(mrun[qs], mx);
;         const float alpha = __builtin_amdgcn_exp2f(mrun[qs] - mn);
;         mrun[qs] = mn;
;         const float mnx = fmaxf(mn, -1e29f);
;         float ps = 0.f;
; #pragma unroll
;         for (int s = 0; s < 4; ++s)
; #pragma unroll
;             for (int i = 0; i < 4; ++i) { const float p = __builtin_amdgcn_exp2f(sc[s][qs][i] - mnx); sc[s][qs][i] = p; ps += p; }
;         lrun[qs] = lrun[qs] * alpha + ps;
; #pragma unroll
;         for (int d = 0; d < 4; ++d) O[d][qs] = O[d][qs] * alpha;
;     }
;     __builtin_amdgcn_s_setprio(1);
; #pragma unroll
;     for (int kk = 0; kk < 2; ++kk) {
;         bf16x8 Pf[2];
; #pragma unroll
;         for (int qs = 0; qs < 2; ++qs) { u32x4 w; w.x = pk2(sc[2 * kk][qs][0], sc[2 * kk][qs][1]); w.y = pk2(sc[2 * kk][qs][2], sc[2 * kk][qs][3]);
;             w.z = pk2(sc[2 * kk + 1][qs][0], sc[2 * kk + 1][qs][1]); w.w = pk2(sc[2 * kk + 1][qs][2], sc[2 * kk + 1][qs][3]); Pf[qs] = __builtin_bit_cast(bf16x8, w); }
.LBB0_1115:
	v_max3_f32 v161, v136, s92, v137
	v_max3_f32 v161, v161, v138, v139
	v_max3_f32 v161, v161, v144, v145
	v_max3_f32 v161, v161, v146, v147
	v_max3_f32 v161, v161, v148, v149
	v_max3_f32 v161, v161, v150, v151
	v_max3_f32 v161, v161, v152, v153
	v_max3_f32 v161, v161, v154, v155
	ds_bpermute_b32 v210, v201, v161
	v_add_u32_e32 v226, 0, v209
	s_waitcnt lgkmcnt(0)
	v_max_f32_e32 v210, v210, v210
	v_max_f32_e32 v161, v161, v210
	ds_bpermute_b32 v210, v202, v161
	s_waitcnt lgkmcnt(0)
	v_max3_f32 v161, v208, v161, v210
	v_max_f32_e32 v210, 0xefa18f08, v161
	v_sub_f32_e32 v138, v138, v210
	v_exp_f32_e32 v213, v138
	v_max3_f32 v138, v124, s92, v125
	v_max3_f32 v138, v138, v126, v127
	v_max3_f32 v138, v138, v128, v129
	v_max3_f32 v138, v138, v130, v131
	v_max3_f32 v138, v138, v132, v133
	v_max3_f32 v138, v138, v134, v135
	v_max3_f32 v138, v138, v140, v141
	v_sub_f32_e32 v136, v136, v210
	v_max3_f32 v138, v138, v142, v143
	v_exp_f32_e32 v209, v136
	v_sub_f32_e32 v136, v144, v210
	ds_bpermute_b32 v144, v201, v138
	v_exp_f32_e32 v217, v136
	v_sub_f32_e32 v136, v145, v210
	v_exp_f32_e32 v219, v136
	v_sub_f32_e32 v136, v146, v210
	s_waitcnt lgkmcnt(0)
	v_max_f32_e32 v144, v144, v144
	v_exp_f32_e32 v221, v136
	v_sub_f32_e32 v136, v147, v210
	v_max_f32_e32 v138, v138, v144
	v_sub_f32_e32 v137, v137, v210
	v_exp_f32_e32 v223, v136
	v_sub_f32_e32 v136, v148, v210
	ds_bpermute_b32 v144, v202, v138
	v_sub_f32_e32 v139, v139, v210
	v_exp_f32_e32 v211, v137
	v_exp_f32_e32 v137, v136
	v_sub_f32_e32 v136, v149, v210
	v_exp_f32_e32 v215, v139
	v_exp_f32_e32 v139, v136
	v_sub_f32_e32 v136, v150, v210
	v_exp_f32_e32 v145, v136
	v_sub_f32_e32 v136, v151, v210
	v_exp_f32_e32 v147, v136
	v_sub_f32_e32 v136, v152, v210
	v_exp_f32_e32 v149, v136
	v_sub_f32_e32 v136, v153, v210
	s_waitcnt lgkmcnt(0)
	v_max3_f32 v227, v207, v138, v144
	v_exp_f32_e32 v151, v136
	v_sub_f32_e32 v136, v154, v210
	v_max_f32_e32 v154, 0xefa18f08, v227
	v_sub_f32_e32 v208, v208, v161
	v_sub_f32_e32 v124, v124, v154
	v_exp_f32_e32 v225, v208
	v_exp_f32_e32 v208, v124
	v_sub_f32_e32 v124, v125, v154
	v_exp_f32_e32 v153, v136
	v_sub_f32_e32 v136, v155, v210
	v_exp_f32_e32 v210, v124
	v_sub_f32_e32 v124, v126, v154
	v_exp_f32_e32 v212, v124
	v_sub_f32_e32 v124, v127, v154
	v_exp_f32_e32 v214, v124
	v_sub_f32_e32 v124, v128, v154
	v_exp_f32_e32 v216, v124
	v_sub_f32_e32 v124, v129, v154
	v_exp_f32_e32 v218, v124
	v_sub_f32_e32 v124, v130, v154
	v_exp_f32_e32 v220, v124
	v_sub_f32_e32 v124, v131, v154
	v_exp_f32_e32 v222, v124
	v_pk_add_f32 v[124:125], v[208:209], 0 op_sel_hi:[1,0]
	v_sub_f32_e32 v126, v132, v154
	v_pk_add_f32 v[124:125], v[210:211], v[124:125]
	v_exp_f32_e32 v155, v136
	v_pk_add_f32 v[124:125], v[212:213], v[124:125]
	v_exp_f32_e32 v136, v126
	v_pk_add_f32 v[124:125], v[214:215], v[124:125]
	v_sub_f32_e32 v126, v133, v154
	v_pk_add_f32 v[124:125], v[216:217], v[124:125]
	v_exp_f32_e32 v138, v126
	v_pk_add_f32 v[124:125], v[218:219], v[124:125]
	v_sub_f32_e32 v126, v134, v154
	v_pk_add_f32 v[124:125], v[220:221], v[124:125]
	v_exp_f32_e32 v144, v126
	v_sub_f32_e32 v126, v135, v154
	v_pk_add_f32 v[124:125], v[222:223], v[124:125]
	v_exp_f32_e32 v146, v126
	v_sub_f32_e32 v126, v140, v154
	v_exp_f32_e32 v148, v126
	v_sub_f32_e32 v126, v141, v154
	v_pk_add_f32 v[124:125], v[136:137], v[124:125]
	v_exp_f32_e32 v150, v126
	v_sub_f32_e32 v126, v142, v154
	v_pk_add_f32 v[124:125], v[138:139], v[124:125]
	v_exp_f32_e32 v152, v126
	v_sub_f32_e32 v126, v143, v154
	v_pk_add_f32 v[124:125], v[144:145], v[124:125]
	v_sub_f32_e32 v207, v207, v227
	v_exp_f32_e32 v154, v126
	v_pk_add_f32 v[124:125], v[146:147], v[124:125]
	v_exp_f32_e32 v224, v207
	v_pk_add_f32 v[124:125], v[148:149], v[124:125]
	v_mov_b32_e32 v126, v225
	v_pk_add_f32 v[124:125], v[150:151], v[124:125]
	v_pk_mul_f32 v[118:119], v[118:119], v[126:127] op_sel_hi:[1,0]
	v_pk_add_f32 v[124:125], v[152:153], v[124:125]
	v_pk_mul_f32 v[116:117], v[116:117], v[126:127] op_sel_hi:[1,0]
	v_pk_add_f32 v[124:125], v[154:155], v[124:125]
	v_pk_mul_f32 v[122:123], v[122:123], v[126:127] op_sel_hi:[1,0]
	v_pk_mul_f32 v[120:121], v[120:121], v[126:127] op_sel_hi:[1,0]
	v_pk_mul_f32 v[114:115], v[114:115], v[126:127] op_sel_hi:[1,0]
	v_pk_mul_f32 v[112:113], v[112:113], v[126:127] op_sel_hi:[1,0]
	v_pk_mul_f32 v[110:111], v[110:111], v[126:127] op_sel_hi:[1,0]
	v_pk_mul_f32 v[108:109], v[108:109], v[126:127] op_sel_hi:[1,0]
	v_pk_fma_f32 v[176:177], v[176:177], v[224:225], v[124:125]
	v_pk_mul_f32 v[106:107], v[106:107], v[224:225] op_sel_hi:[1,0]
	v_pk_mul_f32 v[104:105], v[104:105], v[224:225] op_sel_hi:[1,0]
	v_pk_mul_f32 v[102:103], v[102:103], v[224:225] op_sel_hi:[1,0]
	v_pk_mul_f32 v[100:101], v[100:101], v[224:225] op_sel_hi:[1,0]
	v_pk_mul_f32 v[98:99], v[98:99], v[224:225] op_sel_hi:[1,0]
	v_pk_mul_f32 v[96:97], v[96:97], v[224:225] op_sel_hi:[1,0]
	v_pk_mul_f32 v[94:95], v[94:95], v[224:225] op_sel_hi:[1,0]
	v_pk_mul_f32 v[92:93], v[92:93], v[224:225] op_sel_hi:[1,0]
	ds_read2_b64 v[132:135], v226 offset1:4
	v_cvt_pk_bf16_f32 v124, v209, v211
	v_cvt_pk_bf16_f32 v125, v213, v215
	v_cvt_pk_bf16_f32 v126, v217, v219
	v_cvt_pk_bf16_f32 v127, v221, v223
	v_cvt_pk_bf16_f32 v128, v208, v210
	v_cvt_pk_bf16_f32 v129, v212, v214
	v_cvt_pk_bf16_f32 v130, v216, v218
	v_cvt_pk_bf16_f32 v131, v220, v222
	s_waitcnt lgkmcnt(0)
; #define LAS __attribute__((address_space(3)))
; #define MFMA16(a, b, c) __builtin_amdgcn_mfma_f32_16x16x32_bf16(a, b, c, 0, 0, 0)
; template <int MODE> ...
;     ...
; #pragma unroll
;         for (int d = 0; d < 4; ++d) {
;             const LAS unsigned char* vp = VT + (d * 16) * 144 + (kk * 32) * 2;
;             const s16x4 lo = *(const LAS s16x4*)vp, hi = *(const LAS s16x4*)(vp + 32);
;             const bf16x8 Vf = {lo[0], lo[1], lo[2], lo[3], hi[0], hi[1], hi[2], hi[3]};
; #pragma unroll
;             for (int qs = 0; qs < 2; ++qs) O[d][qs] = MFMA16(Vf, Pf[qs], O[d][qs]);
;             __builtin_amdgcn_sched_barrier(0);
;         }
;     }
; __device__ __forceinline__ void nsa_phase(LAS unsigned char* lds, const Args& a, const bf16_t* z, const bf16_t* KC, const bf16_t* VCT, const bf16_t* VST, const bf16_t* VWT, bf16_t* A2, int ldo, bool merged) {
;     ...
;             for (; j <= cur; ++j) {
;                 __syncthreads();
;                 nsa_commit(lds, pkv, pvv, tidv);
;                 __syncthreads();
;                 if (j < cur) nsa_fetch(pkv, pvv, z + ((size_t)b * SEQ + (j + 1) * 64) * ZLD + ZKW + g * 64, ZLD, VWT + ((size_t)(b * 128 + g * 64)) * SEQ + (j + 1) * 64, SEQ, tidv);
;                 flash_tile<2>(lds, kt_off, vt_off, Qf, O, mrun, lrun, slope, tq, j * 64, selb, l15, g4, (j < cur) && (j > cur - 8));
;             }
	v_mfma_f32_16x16x32_bf16 v[116:119], v[132:135], v[124:127], v[116:119]
	v_mfma_f32_16x16x32_bf16 v[104:107], v[132:135], v[128:131], v[104:107]
	v_add_u32_e32 v140, 0x800, v226
	ds_read2_b64 v[132:135], v140 offset0:32 offset1:36
	s_waitcnt lgkmcnt(0)
	v_mfma_f32_16x16x32_bf16 v[120:123], v[132:135], v[124:127], v[120:123]
	v_mfma_f32_16x16x32_bf16 v[100:103], v[132:135], v[128:131], v[100:103]
	v_add_u32_e32 v141, 0x1000, v226
	ds_read2_b64 v[132:135], v141 offset0:64 offset1:68
	s_waitcnt lgkmcnt(0)
	v_mfma_f32_16x16x32_bf16 v[112:115], v[132:135], v[124:127], v[112:115]
	v_mfma_f32_16x16x32_bf16 v[96:99], v[132:135], v[128:131], v[96:99]
	v_add_u32_e32 v142, 0x1800, v226
	ds_read2_b64 v[132:135], v142 offset0:96 offset1:100
	s_waitcnt lgkmcnt(0)
	v_mfma_f32_16x16x32_bf16 v[108:111], v[132:135], v[124:127], v[108:111]
	v_mfma_f32_16x16x32_bf16 v[92:95], v[132:135], v[128:131], v[92:95]
	ds_read2_b64 v[132:135], v226 offset0:8 offset1:12
	v_cvt_pk_bf16_f32 v124, v137, v139
	v_cvt_pk_bf16_f32 v125, v145, v147
	v_cvt_pk_bf16_f32 v126, v149, v151
	v_cvt_pk_bf16_f32 v127, v153, v155
	v_cvt_pk_bf16_f32 v128, v136, v138
	v_cvt_pk_bf16_f32 v129, v144, v146
	v_cvt_pk_bf16_f32 v130, v148, v150
	v_cvt_pk_bf16_f32 v131, v152, v154
	s_waitcnt lgkmcnt(0)
	v_mfma_f32_16x16x32_bf16 v[116:119], v[132:135], v[124:127], v[116:119]
	v_mfma_f32_16x16x32_bf16 v[104:107], v[132:135], v[128:131], v[104:107]
	ds_read2_b64 v[132:135], v140 offset0:40 offset1:44
	s_waitcnt lgkmcnt(0)
	v_mfma_f32_16x16x32_bf16 v[120:123], v[132:135], v[124:127], v[120:123]
	v_mfma_f32_16x16x32_bf16 v[100:103], v[132:135], v[128:131], v[100:103]
	ds_read2_b64 v[132:135], v141 offset0:72 offset1:76
	s_waitcnt lgkmcnt(0)
	v_mfma_f32_16x16x32_bf16 v[112:115], v[132:135], v[124:127], v[112:115]
	v_mfma_f32_16x16x32_bf16 v[96:99], v[132:135], v[128:131], v[96:99]
	ds_read2_b64 v[132:135], v142 offset0:104 offset1:108
	s_waitcnt lgkmcnt(0)
	v_mfma_f32_16x16x32_bf16 v[108:111], v[132:135], v[124:127], v[108:111]
	v_mfma_f32_16x16x32_bf16 v[92:95], v[132:135], v[128:131], v[92:95]
	s_add_i32 s77, s77, 1
	s_add_i32 s79, s79, 64
	v_subrev_u32_e32 v3, 64, v3
	s_and_b64 vcc, exec, s[74:75]
	v_mov_b32_e32 v208, v161
	v_mov_b32_e32 v207, v227
	s_cbranch_vccnz .LBB0_912

; #define LAS __attribute__((address_space(3)))
; #define MFMA16(a, b, c) __builtin_amdgcn_mfma_f32_16x16x32_bf16(a, b, c, 0, 0, 0)
; template <int MODE> ...
;     ...
;     for (int qs = 0; qs < 2; ++qs) cb[qs] = slope * (float)(key0 + 4 * g4 - tq[qs]) + ((MODE == 1 && !selb[qs]) ? -1e30f : 0.f);
;     __builtin_amdgcn_s_setprio(1);
; #pragma unroll
;     for (int s = 0; s < 4; ++s) {
;         const LAS unsigned char* kp = KT + (s * 16) * 144;
;         const bf16x8 k0 = *(const LAS bf16x8*)kp, k1 = *(const LAS bf16x8*)(kp + 64);
; #pragma unroll
;         for (int qs = 0; qs < 2; ++qs) {
;             f32x4 zz;
; #pragma unroll
;             for (int i = 0; i < 4; ++i) zz[i] = fmaf(slope, (float)(s * 16 + i), cb[qs]);
;             zz = MFMA16(k0, Qf[qs][0], zz);
;             sc[s][qs] = MFMA16(k1, Qf[qs][1], zz);
;         }
;         __builtin_amdgcn_sched_barrier(0);
;     }
;     __builtin_amdgcn_s_setprio(0);
;     if (!full) {
; #pragma unroll
;         for (int qs = 0; qs < 2; ++qs)
; #pragma unroll
;             for (int s = 0; s < 4; ++s)
; #pragma unroll
;                 for (int i = 0; i < 4; ++i) {
;                     const int dist = (tq[qs] - key0 - 4 * g4) - (s * 16 + i);
;                     const bool ok = (MODE == 1) ? (dist >= 0) : (dist >= 0 && dist < 512);
;                     sc[s][qs][i] = ok ? sc[s][qs][i] : -1e30f;
;                 }
.LBB0_1118:
	v_add_u32_e32 v125, s79, v204
	v_cvt_f32_i32_e32 v126, v125
	v_add_u32_e32 v125, -16, v125
	v_cvt_f32_i32_e32 v125, v125
	s_cmp_gt_i32 s77, s69
	s_cselect_b64 s[6:7], -1, 0
	v_mov_b32_e32 v124, v1
	v_mov_b32_e32 v209, v203
	s_and_b64 s[0:1], s[0:1], s[6:7]
	v_fma_f32 v210, v160, v126, 0
	v_add_u32_e32 v215, 0, v124
	v_fma_f32 v214, v160, v125, 0
	ds_read_b128 v[124:127], v215
	v_fma_f32 v128, 0, v160, v210
	v_add_f32_e32 v129, v160, v210
	v_pk_fma_f32 v[130:131], v[162:163], s[56:57], v[210:211] op_sel_hi:[1,1,0]
	v_fma_f32 v132, 0, v160, v214
	v_add_f32_e32 v133, v160, v214
	v_pk_fma_f32 v[134:135], v[162:163], s[56:57], v[214:215] op_sel_hi:[1,1,0]
	s_waitcnt lgkmcnt(0)
	v_mfma_f32_16x16x32_bf16 v[128:131], v[124:127], v[4:7], v[128:131]
	v_mfma_f32_16x16x32_bf16 v[124:127], v[124:127], v[12:15], v[132:135]
	s_nop 2
	ds_read_b128 v[132:135], v215 offset:64
	s_waitcnt lgkmcnt(0)
	v_mfma_f32_16x16x32_bf16 v[136:139], v[132:135], v[8:11], v[128:131]
	v_mfma_f32_16x16x32_bf16 v[124:127], v[132:135], v[16:19], v[124:127]
	s_nop 1
	ds_read_b128 v[128:131], v215 offset:2304
	v_mov_b32_e32 v161, v160
	v_pk_fma_f32 v[132:133], v[164:165], s[88:89], v[210:211] op_sel_hi:[1,1,0]
	v_pk_fma_f32 v[134:135], v[160:161], s[20:21], v[210:211] op_sel_hi:[1,1,0]
	v_pk_fma_f32 v[140:141], v[164:165], s[88:89], v[214:215] op_sel_hi:[1,1,0]
	v_pk_fma_f32 v[142:143], v[160:161], s[20:21], v[214:215] op_sel_hi:[1,1,0]
	s_waitcnt lgkmcnt(0)
	v_mfma_f32_16x16x32_bf16 v[132:135], v[128:131], v[4:7], v[132:135]
	v_mfma_f32_16x16x32_bf16 v[128:131], v[128:131], v[12:15], v[140:143]
	s_nop 2
	ds_read_b128 v[140:143], v215 offset:2368
	s_waitcnt lgkmcnt(0)
	v_mfma_f32_16x16x32_bf16 v[144:147], v[140:143], v[8:11], v[132:135]
	v_mfma_f32_16x16x32_bf16 v[128:131], v[140:143], v[16:19], v[128:131]
	s_nop 1
	ds_read_b128 v[132:135], v215 offset:4608
	ds_read_b128 v[152:155], v215 offset:4672
	v_pk_fma_f32 v[142:143], v[160:161], s[54:55], v[210:211] op_sel_hi:[1,1,0]
	v_pk_fma_f32 v[140:141], v[164:165], s[80:81], v[210:211] op_sel_hi:[1,1,0]
	v_pk_fma_f32 v[150:151], v[160:161], s[54:55], v[214:215] op_sel_hi:[1,1,0]
	v_pk_fma_f32 v[148:149], v[164:165], s[80:81], v[214:215] op_sel_hi:[1,1,0]
	s_waitcnt lgkmcnt(1)
	v_mfma_f32_16x16x32_bf16 v[140:143], v[132:135], v[4:7], v[140:143]
	v_mfma_f32_16x16x32_bf16 v[132:135], v[132:135], v[12:15], v[148:151]
	s_waitcnt lgkmcnt(0)
	v_mfma_f32_16x16x32_bf16 v[148:151], v[152:155], v[8:11], v[140:143]
	v_mfma_f32_16x16x32_bf16 v[132:135], v[152:155], v[16:19], v[132:135]
	s_nop 3
	ds_read_b128 v[140:143], v215 offset:6912
	v_pk_fma_f32 v[154:155], v[160:161], s[44:45], v[210:211] op_sel_hi:[1,1,0]
	v_pk_fma_f32 v[152:153], v[164:165], s[40:41], v[210:211] op_sel_hi:[1,1,0]
	v_pk_fma_f32 v[212:213], v[160:161], s[44:45], v[214:215] op_sel_hi:[1,1,0]
	v_pk_fma_f32 v[210:211], v[164:165], s[40:41], v[214:215] op_sel_hi:[1,1,0]
	s_waitcnt lgkmcnt(0)
	v_mfma_f32_16x16x32_bf16 v[152:155], v[140:143], v[4:7], v[152:155]
	v_mfma_f32_16x16x32_bf16 v[140:143], v[140:143], v[12:15], v[210:213]
	s_nop 2
	ds_read_b128 v[210:213], v215 offset:6976
	s_waitcnt lgkmcnt(0)
	v_mfma_f32_16x16x32_bf16 v[152:155], v[210:213], v[8:11], v[152:155]
	v_mfma_f32_16x16x32_bf16 v[140:143], v[210:213], v[16:19], v[140:143]
	s_and_b64 vcc, exec, s[0:1]
	s_cbranch_vccnz .LBB0_1115
	v_add_u32_e32 v161, 51, v3
	v_cmp_gt_u32_e32 vcc, s35, v161
	v_add_u32_e32 v161, 50, v3
	v_cmp_gt_u32_e64 s[0:1], s35, v161
	v_add_u32_e32 v161, 49, v3
	v_cmp_gt_u32_e64 s[6:7], s35, v161
	v_add_u32_e32 v161, 48, v3
	v_cmp_gt_u32_e64 s[8:9], s35, v161
	v_add_u32_e32 v161, 35, v3
	v_cmp_gt_u32_e64 s[10:11], s35, v161
	v_add_u32_e32 v161, 34, v3
	v_cmp_gt_u32_e64 s[12:13], s35, v161
	v_add_u32_e32 v161, 33, v3
	v_cmp_gt_u32_e64 s[14:15], s35, v161
	v_add_u32_e32 v161, 32, v3
	v_cmp_gt_u32_e64 s[16:17], s35, v161
	v_add_u32_e32 v161, 19, v3
	v_cmp_gt_u32_e64 s[18:19], s35, v161
	v_add_u32_e32 v161, 18, v3
	v_cmp_gt_u32_e64 s[22:23], s35, v161
	v_add_u32_e32 v161, 17, v3
	v_cmp_gt_u32_e64 s[24:25], s35, v161
	v_add_u32_e32 v161, 16, v3
	v_cmp_gt_u32_e64 s[26:27], s35, v161
	v_add_u32_e32 v161, 3, v3
	v_cmp_gt_u32_e64 s[28:29], s35, v161
	v_add_u32_e32 v161, 2, v3
	v_cndmask_b32_e32 v136, v194, v136, vcc
	v_cndmask_b32_e64 v152, v194, v152, s[28:29]
	v_cmp_gt_u32_e64 s[28:29], s35, v161
	v_add_u32_e32 v161, 1, v3
	v_cndmask_b32_e64 v137, v194, v137, s[0:1]
	v_cndmask_b32_e64 v153, v194, v153, s[28:29]
	v_cmp_gt_u32_e64 s[28:29], s35, v161
	v_add_u32_e32 v161, 0x43, v3
	v_cndmask_b32_e64 v138, v194, v138, s[6:7]
	v_cndmask_b32_e64 v154, v194, v154, s[28:29]
	v_cmp_gt_u32_e64 s[28:29], s35, v3
	v_cndmask_b32_e64 v139, v194, v139, s[8:9]
	v_cndmask_b32_e64 v144, v194, v144, s[10:11]
	v_cndmask_b32_e64 v155, v194, v155, s[28:29]
	v_cmp_gt_u32_e64 s[28:29], s35, v161
	v_add_u32_e32 v161, 0x42, v3
	v_cndmask_b32_e64 v145, v194, v145, s[12:13]
	v_cndmask_b32_e64 v124, v194, v124, s[28:29]
	v_cmp_gt_u32_e64 s[28:29], s35, v161
	v_add_u32_e32 v161, 0x41, v3
	v_cndmask_b32_e64 v146, v194, v146, s[14:15]
	v_cndmask_b32_e64 v125, v194, v125, s[28:29]
	v_cmp_gt_u32_e64 s[28:29], s35, v161
	v_add_u32_e32 v161, 64, v3
	v_cndmask_b32_e64 v147, v194, v147, s[16:17]
	v_cndmask_b32_e64 v126, v194, v126, s[28:29]
	v_cmp_gt_u32_e64 s[28:29], s35, v161
	v_cndmask_b32_e64 v148, v194, v148, s[18:19]
	v_cndmask_b32_e64 v149, v194, v149, s[22:23]
	v_cndmask_b32_e64 v150, v194, v150, s[24:25]
	v_cndmask_b32_e64 v151, v194, v151, s[26:27]
	v_cndmask_b32_e64 v127, v194, v127, s[28:29]
	v_cndmask_b32_e32 v128, v194, v128, vcc
	v_cndmask_b32_e64 v129, v194, v129, s[0:1]
	v_cndmask_b32_e64 v130, v194, v130, s[6:7]
	v_cndmask_b32_e64 v131, v194, v131, s[8:9]
	v_cndmask_b32_e64 v132, v194, v132, s[10:11]
	v_cndmask_b32_e64 v133, v194, v133, s[12:13]
	v_cndmask_b32_e64 v134, v194, v134, s[14:15]
	v_cndmask_b32_e64 v135, v194, v135, s[16:17]
	v_cndmask_b32_e64 v140, v194, v140, s[18:19]
	v_cndmask_b32_e64 v141, v194, v141, s[22:23]
	v_cndmask_b32_e64 v142, v194, v142, s[24:25]
	v_cndmask_b32_e64 v143, v194, v143, s[26:27]
	s_branch .LBB0_1115

; #define LAS __attribute__((address_space(3)))
; __device__ __forceinline__ void nsa_phase(LAS unsigned char* lds, const Args& a, const bf16_t* z, const bf16_t* KC, const bf16_t* VCT, const bf16_t* VST, const bf16_t* VWT, bf16_t* A2, int ldo, bool merged) {
;     ...
;     const int nun = merged ? (((int)blockIdx.x < 128) ? 7 : 9) : (2048 * NSA_REP - (int)blockIdx.x + (int)gridDim.x - 1) / (int)gridDim.x;
;     for (int ui = 0; ui < nun; ++ui) {
;         const int uu = merged ? ((ui < 8) ? (int)blockIdx.x + 256 * ui : (int)blockIdx.x - 128 + 1792) : (int)blockIdx.x + ui * (int)gridDim.x;
;         const int unit = uu & 2047;
;         const int bg = unit & 31, qt = ((unit >> 8) & 1) ? ((unit >> 5) ^ 7) : (unit >> 5), b = bg >> 1, g = bg & 1, t0 = qt * 64, cur = qt;
;         const int hq = g * 4 + hr;
;         const float slope = exp2f(-(float)(hq + 1)) * 1.4426950408889634f;
;         const size_t row0 = (size_t)b * SEQ + t0;
;         int l15 = l15_, g4 = g4_; asm volatile("" : "+v"(l15), "+v"(g4));
;         int tidv = tid; asm volatile("" : "+v"(tidv));
;         unsigned kt_off = NS_KT + l15 * 144 + g4 * 16, vt_off = NS_VT + l15 * 144 + g4 * 8;
;         unsigned kcl_off = NS_KCL + l15 * 144 + g4 * 16, vcl_off = NS_VCL + l15 * 528 + g4 * 8;
;         asm volatile("" : "+v"(kcl_off), "+v"(vcl_off));
;         __syncthreads();
;         if (!kc_resident) {
; #pragma unroll
;             for (int it = 0; it < 4; ++it) {
;                 const int row = it * 64 + (tid >> 3), ch = tid & 7;
;                 *(LAS u32x4*)(lds + NS_KCL + row * 144 + ch * 16) = *(const u32x4*)(KC + ((size_t)bg * 256 + row) * 256 + ch * 8);
;                 const int dim = tid >> 3, c16 = (tid & 7) + 8 * it;
;                 *(LAS u32x4*)(lds + NS_VCL + dim * 528 + c16 * 16) = *(const u32x4*)(VCT + ((size_t)bg * 64 + dim) * 256 + c16 * 8);
;             }
;         }
;     ...
;     }
.LBB0_1121:
	s_setprio 0
	v_readlane_b32 s88, v247, 53
	v_readlane_b32 s90, v246, 18
	v_readlane_b32 s92, v246, 13
	s_mov_b64 s[4:5], -1
	v_readlane_b32 s89, v247, 54
	v_readlane_b32 s91, v246, 19
	v_readlane_b32 s93, v246, 14
